# attention O epilogue: bf16 transpose through free LDS + 8 dwordx4 stores per lane instead of 64 short stores; plus SwiGLU packed epilogue
# baseline (speedup 1.0000x reference)
; __device__ __forceinline__ int crow(int r, int hi) { return (r & 3) + 8 * (r >> 2) + 4 * hi; }
; __device__ __forceinline__ unsigned short f2bf(float f) { return (unsigned short)(cvtpk(f, 0.f) & 0xffffu); }
; __device__ __forceinline__ void attn_dense_body(const bf16* Qb, const bf16* __restrict__ Kh, const bf16* __restrict__ Vh, bf16* Ob, int seq, char* lds, const float* __restrict__ qn, int qpos0) {
;     ...
;   if (hi == 0) li_l[r32] = l_reg; asm volatile("s_waitcnt lgkmcnt(0)" ::: "memory");
;   float rli[16];
; #pragma unroll
;   for (int r = 0; r < 16; ++r) rli[r] = __builtin_amdgcn_rcpf(li_l[crow(r, hi)]);
;   bf16* Ow = Ob + (long)(wid * QBLK) * LDO;
; #pragma unroll
;   for (int r = 0; r < 16; ++r) { int orow = crow(r, hi);
; #pragma unroll
;     for (int d0 = 0; d0 < 4; ++d0) Ow[(long)orow * LDO + d0 * 32 + r32] = f2bf(o[d0][r] * rli[r]); }
.LBB0_1029:
	s_or_b64 exec, exec, s[0:1]
	s_waitcnt lgkmcnt(0)
	v_add_u32_e32 v74, v164, v186
	ds_read_b128 v[66:69], v74
	ds_read_b128 v[70:73], v74 offset:32
	ds_read_b128 v[76:79], v74 offset:64
	ds_read_b128 v[80:83], v74 offset:96
	v_lshlrev_b32_e32 v84, 8, v150
	v_and_b32_e32 v89, 0x80, v150
	v_lshl_add_u32 v84, v89, 5, v84
	v_add_u32_e32 v84, 0x8000, v84
	v_lshlrev_b32_e32 v85, 10, v162
	v_lshl_add_u32 v85, v163, 1, v85
	v_add_u32_e32 v85, v85, v84
	v_lshl_add_u32 v86, v162, 5, v163
	v_lshl_add_u32 v87, v86, 4, v84
	v_lshrrev_b32_e32 v88, 4, v86
	v_add_u32_e32 v88, v88, v150
	v_and_b32_e32 v89, 15, v86
	v_lshlrev_b32_e32 v89, 4, v89
	v_lshl_add_u32 v88, v88, 11, v89
	s_waitcnt lgkmcnt(0)
	v_rcp_f32_e32 v66, v66
	v_rcp_f32_e32 v67, v67
	v_rcp_f32_e32 v68, v68
	v_rcp_f32_e32 v69, v69
	v_rcp_f32_e32 v70, v70
	v_rcp_f32_e32 v71, v71
	v_rcp_f32_e32 v72, v72
	v_rcp_f32_e32 v73, v73
	v_rcp_f32_e32 v76, v76
	v_rcp_f32_e32 v77, v77
	v_rcp_f32_e32 v78, v78
	v_rcp_f32_e32 v79, v79
	v_rcp_f32_e32 v80, v80
	v_rcp_f32_e32 v81, v81
	v_rcp_f32_e32 v82, v82
	v_rcp_f32_e32 v83, v83
	v_mul_f32_e32 v90, v2, v66
	v_mul_f32_e32 v91, v18, v66
	v_mul_f32_e32 v92, v34, v66
	v_mul_f32_e32 v93, v50, v66
	v_cvt_pk_bf16_f32 v90, v90, v91
	v_cvt_pk_bf16_f32 v92, v92, v93
	ds_write_b16 v85, v90 offset:0
	ds_write_b16_d16_hi v85, v90 offset:64
	ds_write_b16 v85, v92 offset:128
	ds_write_b16_d16_hi v85, v92 offset:192
	v_mul_f32_e32 v90, v3, v67
	v_mul_f32_e32 v91, v19, v67
	v_mul_f32_e32 v92, v35, v67
	v_mul_f32_e32 v93, v51, v67
	v_cvt_pk_bf16_f32 v90, v90, v91
	v_cvt_pk_bf16_f32 v92, v92, v93
	ds_write_b16 v85, v90 offset:256
	ds_write_b16_d16_hi v85, v90 offset:320
	ds_write_b16 v85, v92 offset:384
	ds_write_b16_d16_hi v85, v92 offset:448
	v_mul_f32_e32 v90, v4, v68
	v_mul_f32_e32 v91, v20, v68
	v_mul_f32_e32 v92, v36, v68
	v_mul_f32_e32 v93, v52, v68
	v_cvt_pk_bf16_f32 v90, v90, v91
	v_cvt_pk_bf16_f32 v92, v92, v93
	ds_write_b16 v85, v90 offset:512
	ds_write_b16_d16_hi v85, v90 offset:576
	ds_write_b16 v85, v92 offset:640
	ds_write_b16_d16_hi v85, v92 offset:704
	v_mul_f32_e32 v90, v5, v69
	v_mul_f32_e32 v91, v21, v69
	v_mul_f32_e32 v92, v37, v69
	v_mul_f32_e32 v93, v53, v69
	v_cvt_pk_bf16_f32 v90, v90, v91
	v_cvt_pk_bf16_f32 v92, v92, v93
	ds_write_b16 v85, v90 offset:768
	ds_write_b16_d16_hi v85, v90 offset:832
	ds_write_b16 v85, v92 offset:896
	ds_write_b16_d16_hi v85, v92 offset:960
	v_mul_f32_e32 v90, v6, v70
	v_mul_f32_e32 v91, v22, v70
	v_mul_f32_e32 v92, v38, v70
	v_mul_f32_e32 v93, v54, v70
	v_cvt_pk_bf16_f32 v90, v90, v91
	v_cvt_pk_bf16_f32 v92, v92, v93
	ds_write_b16 v85, v90 offset:2048
	ds_write_b16_d16_hi v85, v90 offset:2112
	ds_write_b16 v85, v92 offset:2176
	ds_write_b16_d16_hi v85, v92 offset:2240
	v_mul_f32_e32 v90, v7, v71
	v_mul_f32_e32 v91, v23, v71
	v_mul_f32_e32 v92, v39, v71
	v_mul_f32_e32 v93, v55, v71
	v_cvt_pk_bf16_f32 v90, v90, v91
	v_cvt_pk_bf16_f32 v92, v92, v93
	ds_write_b16 v85, v90 offset:2304
	ds_write_b16_d16_hi v85, v90 offset:2368
	ds_write_b16 v85, v92 offset:2432
	ds_write_b16_d16_hi v85, v92 offset:2496
	v_mul_f32_e32 v90, v8, v72
	v_mul_f32_e32 v91, v24, v72
	v_mul_f32_e32 v92, v40, v72
	v_mul_f32_e32 v93, v56, v72
	v_cvt_pk_bf16_f32 v90, v90, v91
	v_cvt_pk_bf16_f32 v92, v92, v93
	ds_write_b16 v85, v90 offset:2560
	ds_write_b16_d16_hi v85, v90 offset:2624
	ds_write_b16 v85, v92 offset:2688
	ds_write_b16_d16_hi v85, v92 offset:2752
	v_mul_f32_e32 v90, v9, v73
	v_mul_f32_e32 v91, v25, v73
	v_mul_f32_e32 v92, v41, v73
	v_mul_f32_e32 v93, v57, v73
	v_cvt_pk_bf16_f32 v90, v90, v91
	v_cvt_pk_bf16_f32 v92, v92, v93
	ds_write_b16 v85, v90 offset:2816
	ds_write_b16_d16_hi v85, v90 offset:2880
	ds_write_b16 v85, v92 offset:2944
	ds_write_b16_d16_hi v85, v92 offset:3008
	v_mul_f32_e32 v90, v10, v76
	v_mul_f32_e32 v91, v26, v76
	v_mul_f32_e32 v92, v42, v76
	v_mul_f32_e32 v93, v58, v76
	v_cvt_pk_bf16_f32 v90, v90, v91
	v_cvt_pk_bf16_f32 v92, v92, v93
	ds_write_b16 v85, v90 offset:4096
	ds_write_b16_d16_hi v85, v90 offset:4160
	ds_write_b16 v85, v92 offset:4224
	ds_write_b16_d16_hi v85, v92 offset:4288
	v_mul_f32_e32 v90, v11, v77
	v_mul_f32_e32 v91, v27, v77
	v_mul_f32_e32 v92, v43, v77
	v_mul_f32_e32 v93, v59, v77
	v_cvt_pk_bf16_f32 v90, v90, v91
	v_cvt_pk_bf16_f32 v92, v92, v93
	ds_write_b16 v85, v90 offset:4352
	ds_write_b16_d16_hi v85, v90 offset:4416
	ds_write_b16 v85, v92 offset:4480
	ds_write_b16_d16_hi v85, v92 offset:4544
	v_mul_f32_e32 v90, v12, v78
	v_mul_f32_e32 v91, v28, v78
	v_mul_f32_e32 v92, v44, v78
	v_mul_f32_e32 v93, v60, v78
	v_cvt_pk_bf16_f32 v90, v90, v91
	v_cvt_pk_bf16_f32 v92, v92, v93
	ds_write_b16 v85, v90 offset:4608
	ds_write_b16_d16_hi v85, v90 offset:4672
	ds_write_b16 v85, v92 offset:4736
	ds_write_b16_d16_hi v85, v92 offset:4800
	v_mul_f32_e32 v90, v13, v79
	v_mul_f32_e32 v91, v29, v79
	v_mul_f32_e32 v92, v45, v79
	v_mul_f32_e32 v93, v61, v79
	v_cvt_pk_bf16_f32 v90, v90, v91
	v_cvt_pk_bf16_f32 v92, v92, v93
	ds_write_b16 v85, v90 offset:4864
	ds_write_b16_d16_hi v85, v90 offset:4928
	ds_write_b16 v85, v92 offset:4992
	ds_write_b16_d16_hi v85, v92 offset:5056
	v_mul_f32_e32 v90, v14, v80
	v_mul_f32_e32 v91, v30, v80
	v_mul_f32_e32 v92, v46, v80
	v_mul_f32_e32 v93, v62, v80
	v_cvt_pk_bf16_f32 v90, v90, v91
	v_cvt_pk_bf16_f32 v92, v92, v93
	ds_write_b16 v85, v90 offset:6144
	ds_write_b16_d16_hi v85, v90 offset:6208
	ds_write_b16 v85, v92 offset:6272
	ds_write_b16_d16_hi v85, v92 offset:6336
	v_mul_f32_e32 v90, v15, v81
	v_mul_f32_e32 v91, v31, v81
	v_mul_f32_e32 v92, v47, v81
	v_mul_f32_e32 v93, v63, v81
	v_cvt_pk_bf16_f32 v90, v90, v91
	v_cvt_pk_bf16_f32 v92, v92, v93
	ds_write_b16 v85, v90 offset:6400
	ds_write_b16_d16_hi v85, v90 offset:6464
	ds_write_b16 v85, v92 offset:6528
	ds_write_b16_d16_hi v85, v92 offset:6592
	v_mul_f32_e32 v90, v16, v82
	v_mul_f32_e32 v91, v32, v82
	v_mul_f32_e32 v92, v48, v82
	v_mul_f32_e32 v93, v64, v82
	v_cvt_pk_bf16_f32 v90, v90, v91
	v_cvt_pk_bf16_f32 v92, v92, v93
	ds_write_b16 v85, v90 offset:6656
	ds_write_b16_d16_hi v85, v90 offset:6720
	ds_write_b16 v85, v92 offset:6784
	ds_write_b16_d16_hi v85, v92 offset:6848
	v_mul_f32_e32 v90, v17, v83
	v_mul_f32_e32 v91, v33, v83
	v_mul_f32_e32 v92, v49, v83
	v_mul_f32_e32 v93, v65, v83
	v_cvt_pk_bf16_f32 v90, v90, v91
	v_cvt_pk_bf16_f32 v92, v92, v93
	ds_write_b16 v85, v90 offset:6912
	ds_write_b16_d16_hi v85, v90 offset:6976
	ds_write_b16 v85, v92 offset:7040
	ds_write_b16_d16_hi v85, v92 offset:7104
	s_waitcnt lgkmcnt(0)
; __device__ __forceinline__ int crow(int r, int hi) { return (r & 3) + 8 * (r >> 2) + 4 * hi; }
; __device__ __forceinline__ unsigned short f2bf(float f) { return (unsigned short)(cvtpk(f, 0.f) & 0xffffu); }
; __device__ __forceinline__ void attn_dense_body(const bf16* Qb, const bf16* __restrict__ Kh, const bf16* __restrict__ Vh, bf16* Ob, int seq, char* lds, const float* __restrict__ qn, int qpos0) {
;     ...
;   bf16* Ow = Ob + (long)(wid * QBLK) * LDO;
; #pragma unroll
;   for (int r = 0; r < 16; ++r) { int orow = crow(r, hi);
; #pragma unroll
;     for (int d0 = 0; d0 < 4; ++d0) Ow[(long)orow * LDO + d0 * 32 + r32] = f2bf(o[d0][r] * rli[r]); }
;   __syncthreads();
	ds_read_b128 v[2:5], v87
	ds_read_b128 v[6:9], v87 offset:1024
	ds_read_b128 v[10:13], v87 offset:2048
	ds_read_b128 v[14:17], v87 offset:3072
	ds_read_b128 v[18:21], v87 offset:4096
	ds_read_b128 v[22:25], v87 offset:5120
	ds_read_b128 v[26:29], v87 offset:6144
	ds_read_b128 v[30:33], v87 offset:7168
	s_waitcnt lgkmcnt(7)
	global_store_dwordx4 v88, v[2:5], s[18:19]
	s_nop 1
	v_add_u32_e32 v88, 0x2000, v88
	s_waitcnt lgkmcnt(6)
	global_store_dwordx4 v88, v[6:9], s[18:19]
	s_nop 1
	v_add_u32_e32 v88, 0x2000, v88
	s_waitcnt lgkmcnt(5)
	global_store_dwordx4 v88, v[10:13], s[18:19]
	s_nop 1
	v_add_u32_e32 v88, 0x2000, v88
	s_waitcnt lgkmcnt(4)
	global_store_dwordx4 v88, v[14:17], s[18:19]
	s_nop 1
	v_add_u32_e32 v88, 0x2000, v88
	s_waitcnt lgkmcnt(3)
	global_store_dwordx4 v88, v[18:21], s[18:19]
	s_nop 1
	v_add_u32_e32 v88, 0x2000, v88
	s_waitcnt lgkmcnt(2)
	global_store_dwordx4 v88, v[22:25], s[18:19]
	s_nop 1
	v_add_u32_e32 v88, 0x2000, v88
	s_waitcnt lgkmcnt(1)
	global_store_dwordx4 v88, v[26:29], s[18:19]
	s_nop 1
	v_add_u32_e32 v88, 0x2000, v88
	s_waitcnt lgkmcnt(0)
	global_store_dwordx4 v88, v[30:33], s[18:19]
	v_ashrrev_i32_e32 v151, 31, v150
	v_lshlrev_b32_e32 v186, 1, v163
	s_waitcnt vmcnt(63) expcnt(7) lgkmcnt(15)
	s_barrier
	s_branch .LBB0_1013
